# prep conv stage: s_setprio 1 for the two waves that also do the per-row decay work, reset before the stage barrier
# baseline (speedup 1.0000x reference)
.LBB0_594:
	s_or_b64 exec, exec, s[0:1]
	v_lshlrev_b32_e32 v0, 2, v32
	v_lshl_add_u64 v[34:35], s[78:79], 0, v[0:1]
	s_movk_i32 s0, 0x3000
	v_add_co_u32_e32 v32, vcc, s0, v34
	s_mov_b64 s[0:1], 0x6000
	global_load_dwordx4 v[26:29], v0, s[78:79] offset:16
	global_load_dwordx4 v[38:41], v0, s[78:79]
	v_addc_co_u32_e32 v33, vcc, 0, v35, vcc
	v_lshl_add_u64 v[36:37], v[34:35], 0, s[0:1]
	s_movk_i32 s0, 0x6000
	v_sub_u32_e32 v0, 60, v168
	v_lshl_add_u64 v[30:31], v[34:35], 0, s[24:25]
	v_add_co_u32_e32 v34, vcc, s0, v34
	v_cndmask_b32_e64 v0, v0, v168, s[44:45]
	v_and_b32_e32 v150, 56, v150
	s_mov_b32 s0, 0x7ffffff8
	v_bitop3_b32 v150, v0, v150, s0 bitop3:0x6c
	s_cmp_lg_u64 s[46:47], 0
	s_cbranch_scc0 .Lprio_skip
	s_setprio 1
.Lprio_skip:
	s_waitcnt vmcnt(14)
	v_lshlrev_b32_e32 v154, 16, v145
	v_and_b32_e32 v155, 0xffff0000, v145
	v_and_or_b32 v169, v0, 4, v150
	v_lshlrev_b32_e32 v150, 16, v133
	v_and_b32_e32 v151, 0xffff0000, v133
	s_waitcnt vmcnt(10)
	v_pk_mul_f32 v[152:153], v[124:125], v[154:155]
	v_lshlrev_b32_e32 v172, 16, v132
	v_pk_fma_f32 v[152:153], v[120:121], v[150:151], v[152:153]
	v_lshlrev_b32_e32 v150, 16, v141
	v_and_b32_e32 v151, 0xffff0000, v141
	s_waitcnt vmcnt(8)
	v_pk_fma_f32 v[152:153], v[128:129], v[150:151], v[152:153]
	v_and_b32_e32 v173, 0xffff0000, v132
	v_mul_f32_e32 v0, 0xbfb8aa3b, v152
	v_exp_f32_e32 v133, v0
	v_mul_f32_e32 v0, 0xbfb8aa3b, v153
	v_exp_f32_e32 v141, v0
	v_lshlrev_b32_e32 v132, 16, v144
	v_add_f32_e32 v133, 1.0, v133
	v_rcp_f32_e32 v170, v133
	v_add_f32_e32 v133, 1.0, v141
	v_rcp_f32_e32 v171, v133
	v_and_b32_e32 v133, 0xffff0000, v144
	v_lshlrev_b32_e32 v144, 16, v140
	v_and_b32_e32 v145, 0xffff0000, v140
	v_pk_mul_f32 v[140:141], v[122:123], v[132:133]
	v_lshlrev_b32_e32 v176, 16, v143
	v_pk_fma_f32 v[140:141], v[118:119], v[172:173], v[140:141]
	v_and_b32_e32 v177, 0xffff0000, v143
	v_pk_fma_f32 v[172:173], v[126:127], v[144:145], v[140:141]
	v_lshlrev_b32_e32 v174, 16, v131
	v_mul_f32_e32 v140, 0xbfb8aa3b, v172
	v_exp_f32_e32 v140, v140
	v_mul_f32_e32 v141, 0xbfb8aa3b, v173
	v_exp_f32_e32 v141, v141
	v_and_b32_e32 v175, 0xffff0000, v131
	v_add_f32_e32 v140, 1.0, v140
	v_pk_mul_f32 v[178:179], v[112:113], v[176:177]
	v_pk_mul_f32 v[170:171], v[152:153], v[170:171]
	v_rcp_f32_e32 v152, v140
	v_add_f32_e32 v153, 1.0, v141
	v_lshlrev_b32_e32 v140, 16, v139
	v_and_b32_e32 v141, 0xffff0000, v139
	v_pk_fma_f32 v[174:175], v[104:105], v[174:175], v[178:179]
	v_rcp_f32_e32 v153, v153
	v_pk_fma_f32 v[174:175], v[116:117], v[140:141], v[174:175]
	v_pk_mul_f32 v[184:185], v[124:125], v[150:151]
	v_mul_f32_e32 v131, 0xbfb8aa3b, v174
	v_exp_f32_e32 v131, v131
	v_mul_f32_e32 v139, 0xbfb8aa3b, v175
	v_exp_f32_e32 v139, v139
	v_pk_mul_f32 v[172:173], v[172:173], v[152:153]
	v_add_f32_e32 v131, 1.0, v131
	v_rcp_f32_e32 v178, v131
	v_add_f32_e32 v131, 1.0, v139
	v_rcp_f32_e32 v179, v131
	v_and_b32_e32 v131, 0xffff0000, v142
	v_lshlrev_b32_e32 v152, 16, v138
	v_and_b32_e32 v153, 0xffff0000, v138
	v_pk_mul_f32 v[174:175], v[174:175], v[178:179]
	v_lshlrev_b32_e32 v178, 16, v130
	v_and_b32_e32 v179, 0xffff0000, v130
	v_lshlrev_b32_e32 v130, 16, v142
	v_pk_mul_f32 v[138:139], v[110:111], v[130:131]
	v_pk_fma_f32 v[184:185], v[120:121], v[154:155], v[184:185]
	v_pk_fma_f32 v[138:139], v[102:103], v[178:179], v[138:139]
	v_lshlrev_b32_e32 v154, 16, v137
	v_pk_fma_f32 v[138:139], v[114:115], v[152:153], v[138:139]
	v_and_b32_e32 v155, 0xffff0000, v137
	v_mul_f32_e32 v142, 0xbfb8aa3b, v138
	v_mul_f32_e32 v143, 0xbfb8aa3b, v139
	v_exp_f32_e32 v142, v142
	v_exp_f32_e32 v143, v143
	v_pk_fma_f32 v[184:185], v[128:129], v[154:155], v[184:185]
	v_pk_mul_f32 v[192:193], v[112:113], v[140:141]
	v_mul_f32_e32 v137, 0xbfb8aa3b, v184
	v_exp_f32_e32 v137, v137
	v_mul_f32_e32 v186, 0xbfb8aa3b, v185
	v_add_f32_e32 v142, 1.0, v142
	v_add_f32_e32 v143, 1.0, v143
	v_exp_f32_e32 v187, v186
	v_rcp_f32_e32 v142, v142
	v_rcp_f32_e32 v143, v143
	v_add_f32_e32 v137, 1.0, v137
	v_rcp_f32_e32 v186, v137
	v_add_f32_e32 v137, 1.0, v187
	v_rcp_f32_e32 v187, v137
	v_pk_mul_f32 v[188:189], v[138:139], v[142:143]
	v_lshlrev_b32_e32 v142, 16, v136
	v_and_b32_e32 v143, 0xffff0000, v136
	v_pk_mul_f32 v[136:137], v[122:123], v[144:145]
	v_lshlrev_b32_e32 v138, 16, v135
	v_pk_fma_f32 v[132:133], v[118:119], v[132:133], v[136:137]
	v_and_b32_e32 v139, 0xffff0000, v135
	v_pk_fma_f32 v[132:133], v[126:127], v[142:143], v[132:133]
	v_pk_fma_f32 v[176:177], v[104:105], v[176:177], v[192:193]
	v_mul_f32_e32 v136, 0xbfb8aa3b, v132
	v_mul_f32_e32 v137, 0xbfb8aa3b, v133
	v_exp_f32_e32 v136, v136
	v_exp_f32_e32 v137, v137
	v_pk_fma_f32 v[176:177], v[116:117], v[138:139], v[176:177]
	v_pk_mul_f32 v[190:191], v[188:189], v[188:189]
	v_add_f32_e32 v136, 1.0, v136
	v_add_f32_e32 v137, 1.0, v137
	v_mul_f32_e32 v135, 0xbfb8aa3b, v176
	v_rcp_f32_e32 v136, v136
	v_rcp_f32_e32 v137, v137
	v_exp_f32_e32 v135, v135
	v_mul_f32_e32 v192, 0xbfb8aa3b, v177
	v_exp_f32_e32 v206, v192
	v_pk_mul_f32 v[192:193], v[132:133], v[136:137]
	v_add_f32_e32 v132, 1.0, v135
	v_lshlrev_b32_e32 v136, 16, v134
	v_and_b32_e32 v137, 0xffff0000, v134
	v_pk_mul_f32 v[134:135], v[110:111], v[152:153]
	v_add_f32_e32 v133, 1.0, v206
	v_pk_fma_f32 v[130:131], v[102:103], v[130:131], v[134:135]
	v_rcp_f32_e32 v132, v132
	v_pk_fma_f32 v[130:131], v[114:115], v[136:137], v[130:131]
	v_rcp_f32_e32 v133, v133
	v_mul_f32_e32 v134, 0xbfb8aa3b, v130
	v_mul_f32_e32 v135, 0xbfb8aa3b, v131
	v_exp_f32_e32 v134, v134
	v_exp_f32_e32 v135, v135
	v_pk_mul_f32 v[176:177], v[176:177], v[132:133]
	v_pk_mul_f32 v[178:179], v[174:175], v[174:175]
	v_add_f32_e32 v134, 1.0, v134
	v_add_f32_e32 v135, 1.0, v135
	v_rcp_f32_e32 v134, v134
	v_rcp_f32_e32 v135, v135
	v_pk_mul_f32 v[132:133], v[176:177], v[176:177]
	v_mov_b32_e32 v209, v190
	v_pk_mul_f32 v[182:183], v[172:173], v[172:173]
	v_pk_mul_f32 v[130:131], v[130:131], v[134:135]
	v_pk_mul_f32 v[206:207], v[192:193], v[192:193]
	v_pk_mul_f32 v[134:135], v[130:131], v[130:131]
	v_pk_mul_f32 v[184:185], v[184:185], v[186:187]
	v_mov_b32_e32 v208, v134
	v_mov_b32_e32 v190, v135
	v_pk_add_f32 v[134:135], v[208:209], v[190:191]
	v_mov_b32_e32 v190, v132
	v_mov_b32_e32 v191, v178
	v_pk_add_f32 v[134:135], v[190:191], v[134:135]
	v_mov_b32_e32 v178, v133
	v_pk_add_f32 v[132:133], v[178:179], v[134:135]
	v_mov_b32_e32 v134, v206
	v_mov_b32_e32 v135, v182
	v_pk_mul_f32 v[180:181], v[170:171], v[170:171]
	v_pk_mul_f32 v[186:187], v[184:185], v[184:185]
	v_pk_add_f32 v[132:133], v[134:135], v[132:133]
	v_mov_b32_e32 v182, v207
	v_pk_add_f32 v[132:133], v[182:183], v[132:133]
	v_mov_b32_e32 v134, v186
	v_mov_b32_e32 v135, v180
	v_pk_add_f32 v[132:133], v[134:135], v[132:133]
	v_mov_b32_e32 v180, v187
	v_pk_add_f32 v[132:133], v[180:181], v[132:133]
	s_mov_b32 s2, 0x358637bd
	v_addc_co_u32_e32 v35, vcc, 0, v35, vcc
	v_mov_b32_dpp v135, v133 quad_perm:[1,0,3,2] row_mask:0xf bank_mask:0xf bound_ctrl:1
	v_mov_b32_dpp v134, v132 quad_perm:[1,0,3,2] row_mask:0xf bank_mask:0xf bound_ctrl:1
	v_pk_add_f32 v[132:133], v[132:133], v[134:135]
	v_sub_u32_e32 v203, 63, v168
	v_lshl_add_u32 v0, v167, 1, v146
	v_mov_b32_dpp v135, v133 quad_perm:[2,3,0,1] row_mask:0xf bank_mask:0xf bound_ctrl:1
	v_mov_b32_dpp v134, v132 quad_perm:[2,3,0,1] row_mask:0xf bank_mask:0xf bound_ctrl:1
	v_pk_add_f32 v[132:133], v[132:133], v[134:135]
	global_load_dwordx4 v[42:45], v[32:33], off
	s_nop 0
	global_load_dwordx4 v[30:33], v[30:31], off offset:16
	v_mov_b32_dpp v135, v133 row_half_mirror row_mask:0xf bank_mask:0xf bound_ctrl:1
	v_mov_b32_dpp v134, v132 row_half_mirror row_mask:0xf bank_mask:0xf bound_ctrl:1
	v_pk_add_f32 v[132:133], v[132:133], v[134:135]
	global_load_dwordx4 v[46:49], v[34:35], off
	s_nop 0
	global_load_dwordx4 v[34:37], v[36:37], off offset:16
	v_mov_b32_dpp v135, v133 row_mirror row_mask:0xf bank_mask:0xf bound_ctrl:1
	v_mov_b32_dpp v134, v132 row_mirror row_mask:0xf bank_mask:0xf bound_ctrl:1
	v_pk_add_f32 v[132:133], v[132:133], v[134:135]
	v_and_b32_e32 v160, 63, v148
	v_pk_add_f32 v[134:135], v[132:133], s[2:3] op_sel_hi:[1,0]
	s_nop 0
	v_mul_f32_e32 v132, 0x4b800000, v135
	v_cmp_gt_f32_e32 vcc, s72, v135
	s_nop 1
	v_cndmask_b32_e32 v132, v135, v132, vcc
	v_rsq_f32_e32 v135, v132
	v_cndmask_b32_e64 v132, v203, v168, s[44:45]
	v_mad_u64_u32 v[132:133], s[0:1], v132, s14, v[0:1]
	v_mul_f32_e32 v133, 0x45800000, v135
	v_cndmask_b32_e32 v178, v135, v133, vcc
	v_mul_f32_e32 v133, 0x4b800000, v134
	v_cmp_gt_f32_e32 vcc, s72, v134
	v_pk_mul_f32 v[180:181], v[188:189], v[178:179] op_sel_hi:[1,0]
	v_pk_mul_f32 v[174:175], v[174:175], v[178:179] op_sel_hi:[1,0]
	v_cndmask_b32_e32 v133, v134, v133, vcc
	v_rsq_f32_e32 v133, v133
	v_pk_mul_f32 v[172:173], v[172:173], v[178:179] op_sel_hi:[1,0]
	v_pk_mul_f32 v[178:179], v[170:171], v[178:179] op_sel_hi:[1,0]
	v_cvt_pk_bf16_f32 v170, v180, v181
	v_mul_f32_e32 v134, 0x45800000, v133
	v_cvt_pk_bf16_f32 v171, v174, v175
	v_cvt_pk_bf16_f32 v172, v172, v173
	v_cvt_pk_bf16_f32 v173, v178, v179
	v_cndmask_b32_e32 v134, v133, v134, vcc
	ds_write_b128 v132, v[170:173]
	v_pk_mul_f32 v[130:131], v[130:131], v[134:135] op_sel_hi:[1,0]
	v_pk_mul_f32 v[172:173], v[176:177], v[134:135] op_sel_hi:[1,0]
	v_pk_mul_f32 v[174:175], v[192:193], v[134:135] op_sel_hi:[1,0]
	v_pk_mul_f32 v[134:135], v[184:185], v[134:135] op_sel_hi:[1,0]
	v_or_b32_e32 v133, 1, v168
	v_cvt_pk_bf16_f32 v171, v172, v173
	v_cvt_pk_bf16_f32 v173, v134, v135
	v_pk_mul_f32 v[134:135], v[124:125], v[154:155]
	v_sub_u32_e32 v170, 63, v133
	v_pk_fma_f32 v[134:135], v[120:121], v[150:151], v[134:135]
	v_lshlrev_b32_e32 v150, 16, v109
	v_and_b32_e32 v151, 0xffff0000, v109
	v_cndmask_b32_e64 v133, v170, v133, s[44:45]
	v_pk_fma_f32 v[134:135], v[128:129], v[150:151], v[134:135]
	v_pk_mul_f32 v[124:125], v[124:125], v[150:151]
	v_cvt_pk_bf16_f32 v170, v130, v131
	v_mad_u64_u32 v[130:131], s[0:1], v133, s14, v[0:1]
	v_mul_f32_e32 v109, 0xbfb8aa3b, v134
	v_pk_fma_f32 v[120:121], v[120:121], v[154:155], v[124:125]
	v_lshlrev_b32_e32 v124, 16, v101
	v_and_b32_e32 v125, 0xffff0000, v101
	v_exp_f32_e32 v109, v109
	v_mul_f32_e32 v131, 0xbfb8aa3b, v135
	v_pk_fma_f32 v[120:121], v[128:129], v[124:125], v[120:121]
	v_exp_f32_e32 v131, v131
	v_mul_f32_e32 v101, 0xbfb8aa3b, v120
	v_exp_f32_e32 v101, v101
	v_mul_f32_e32 v124, 0xbfb8aa3b, v121
	v_exp_f32_e32 v125, v124
	v_cvt_pk_bf16_f32 v172, v174, v175
	v_add_f32_e32 v109, 1.0, v109
	ds_write_b128 v130, v[170:173]
	v_rcp_f32_e32 v170, v109
	v_add_f32_e32 v109, 1.0, v131
	v_rcp_f32_e32 v171, v109
	v_lshlrev_b32_e32 v172, 16, v108
	v_and_b32_e32 v173, 0xffff0000, v108
	v_pk_mul_f32 v[108:109], v[122:123], v[142:143]
	v_add_f32_e32 v101, 1.0, v101
	v_pk_fma_f32 v[108:109], v[118:119], v[144:145], v[108:109]
	v_rcp_f32_e32 v124, v101
	v_add_f32_e32 v101, 1.0, v125
	v_pk_fma_f32 v[108:109], v[126:127], v[172:173], v[108:109]
	v_rcp_f32_e32 v125, v101
	v_mul_f32_e32 v131, 0xbfb8aa3b, v108
	v_exp_f32_e32 v131, v131
	v_mul_f32_e32 v133, 0xbfb8aa3b, v109
	v_exp_f32_e32 v133, v133
	v_pk_mul_f32 v[174:175], v[112:113], v[138:139]
	v_pk_mul_f32 v[134:135], v[134:135], v[170:171]
	v_lshlrev_b32_e32 v170, 16, v107
	v_and_b32_e32 v171, 0xffff0000, v107
	v_pk_fma_f32 v[140:141], v[104:105], v[140:141], v[174:175]
	v_pk_mul_f32 v[120:121], v[120:121], v[124:125]
	v_lshlrev_b32_e32 v124, 16, v100
	v_and_b32_e32 v125, 0xffff0000, v100
	v_pk_mul_f32 v[100:101], v[122:123], v[172:173]
	v_pk_fma_f32 v[140:141], v[116:117], v[170:171], v[140:141]
	v_pk_fma_f32 v[100:101], v[118:119], v[142:143], v[100:101]
	v_add_f32_e32 v131, 1.0, v131
	v_mul_f32_e32 v107, 0xbfb8aa3b, v140
	v_pk_fma_f32 v[100:101], v[126:127], v[124:125], v[100:101]
	v_rcp_f32_e32 v144, v131
	v_add_f32_e32 v131, 1.0, v133
	v_exp_f32_e32 v107, v107
	v_mul_f32_e32 v133, 0xbfb8aa3b, v141
	v_mul_f32_e32 v118, 0xbfb8aa3b, v100
	v_exp_f32_e32 v133, v133
	v_exp_f32_e32 v122, v118
	v_mul_f32_e32 v118, 0xbfb8aa3b, v101
	v_exp_f32_e32 v123, v118
	v_pk_mul_f32 v[112:113], v[112:113], v[170:171]
	v_lshlrev_b32_e32 v124, 16, v99
	v_and_b32_e32 v125, 0xffff0000, v99
	v_pk_fma_f32 v[104:105], v[104:105], v[138:139], v[112:113]
	v_add_f32_e32 v107, 1.0, v107
	v_pk_fma_f32 v[104:105], v[116:117], v[124:125], v[104:105]
	v_rcp_f32_e32 v174, v107
	v_add_f32_e32 v107, 1.0, v133
	v_mul_f32_e32 v99, 0xbfb8aa3b, v104
	v_rcp_f32_e32 v175, v107
	v_add_f32_e32 v122, 1.0, v122
	v_add_f32_e32 v123, 1.0, v123
	v_exp_f32_e32 v99, v99
	v_mul_f32_e32 v112, 0xbfb8aa3b, v105
	v_rcp_f32_e32 v122, v122
	v_rcp_f32_e32 v123, v123
	v_exp_f32_e32 v116, v112
	v_pk_mul_f32 v[140:141], v[140:141], v[174:175]
	v_lshlrev_b32_e32 v174, 16, v106
	v_and_b32_e32 v175, 0xffff0000, v106
	v_pk_mul_f32 v[106:107], v[110:111], v[136:137]
	v_add_f32_e32 v99, 1.0, v99
	v_pk_fma_f32 v[106:107], v[102:103], v[152:153], v[106:107]
	v_pk_mul_f32 v[112:113], v[100:101], v[122:123]
	v_rcp_f32_e32 v100, v99
	v_add_f32_e32 v101, 1.0, v116
	v_lshlrev_b32_e32 v116, 16, v98
	v_and_b32_e32 v117, 0xffff0000, v98
	v_pk_mul_f32 v[98:99], v[110:111], v[174:175]
	v_pk_fma_f32 v[106:107], v[114:115], v[174:175], v[106:107]
	v_pk_fma_f32 v[98:99], v[102:103], v[136:137], v[98:99]
	v_rcp_f32_e32 v145, v131
	v_mul_f32_e32 v131, 0xbfb8aa3b, v106
	v_pk_fma_f32 v[98:99], v[114:115], v[116:117], v[98:99]
	v_exp_f32_e32 v131, v131
	v_mul_f32_e32 v133, 0xbfb8aa3b, v107
	v_mul_f32_e32 v102, 0xbfb8aa3b, v98
	v_mul_f32_e32 v103, 0xbfb8aa3b, v99
	v_exp_f32_e32 v133, v133
	v_exp_f32_e32 v102, v102
	v_exp_f32_e32 v103, v103
	v_add_f32_e32 v131, 1.0, v131
	v_rcp_f32_e32 v178, v131
	v_add_f32_e32 v131, 1.0, v133
	v_add_f32_e32 v102, 1.0, v102
	v_add_f32_e32 v103, 1.0, v103
	v_rcp_f32_e32 v179, v131
	v_rcp_f32_e32 v102, v102
	v_rcp_f32_e32 v103, v103
	v_rcp_f32_e32 v101, v101
	v_pk_mul_f32 v[106:107], v[106:107], v[178:179]
	v_pk_mul_f32 v[152:153], v[140:141], v[140:141]
	v_pk_mul_f32 v[114:115], v[98:99], v[102:103]
	v_pk_mul_f32 v[128:129], v[106:107], v[106:107]
	v_pk_mul_f32 v[104:105], v[104:105], v[100:101]
	v_pk_mul_f32 v[98:99], v[114:115], v[114:115]
	v_pk_mul_f32 v[100:101], v[104:105], v[104:105]
	v_mov_b32_e32 v102, v98
	v_mov_b32_e32 v103, v128
	v_mov_b32_e32 v128, v99
	v_pk_mul_f32 v[108:109], v[108:109], v[144:145]
	v_pk_add_f32 v[98:99], v[102:103], v[128:129]
	v_mov_b32_e32 v102, v100
	v_mov_b32_e32 v103, v152
	v_pk_mul_f32 v[144:145], v[108:109], v[108:109]
	v_pk_mul_f32 v[110:111], v[112:113], v[112:113]
	v_pk_add_f32 v[98:99], v[102:103], v[98:99]
	v_mov_b32_e32 v152, v101
	v_pk_add_f32 v[98:99], v[152:153], v[98:99]
	v_mov_b32_e32 v100, v110
	v_mov_b32_e32 v101, v144
	v_pk_mul_f32 v[176:177], v[134:135], v[134:135]
	v_pk_mul_f32 v[118:119], v[120:121], v[120:121]
	v_pk_add_f32 v[98:99], v[100:101], v[98:99]
	v_mov_b32_e32 v144, v111
	v_pk_add_f32 v[98:99], v[144:145], v[98:99]
	v_mov_b32_e32 v100, v118
	v_mov_b32_e32 v101, v176
	v_pk_add_f32 v[98:99], v[100:101], v[98:99]
	v_mov_b32_e32 v176, v119
	v_pk_add_f32 v[98:99], v[176:177], v[98:99]
	v_or_b32_e32 v131, 2, v168
	v_sub_u32_e32 v133, 63, v131
	v_mov_b32_dpp v101, v99 quad_perm:[1,0,3,2] row_mask:0xf bank_mask:0xf bound_ctrl:1
	v_mov_b32_dpp v100, v98 quad_perm:[1,0,3,2] row_mask:0xf bank_mask:0xf bound_ctrl:1
	v_pk_add_f32 v[98:99], v[98:99], v[100:101]
	v_lshlrev_b32_e32 v118, 16, v89
	v_and_b32_e32 v119, 0xffff0000, v89
	v_mov_b32_dpp v101, v99 quad_perm:[2,3,0,1] row_mask:0xf bank_mask:0xf bound_ctrl:1
	v_mov_b32_dpp v100, v98 quad_perm:[2,3,0,1] row_mask:0xf bank_mask:0xf bound_ctrl:1
	v_pk_add_f32 v[98:99], v[98:99], v[100:101]
	s_nop 1
	v_mov_b32_dpp v101, v99 row_half_mirror row_mask:0xf bank_mask:0xf bound_ctrl:1
	v_mov_b32_dpp v100, v98 row_half_mirror row_mask:0xf bank_mask:0xf bound_ctrl:1
	v_pk_add_f32 v[98:99], v[98:99], v[100:101]
	s_nop 1
	v_mov_b32_dpp v101, v99 row_mirror row_mask:0xf bank_mask:0xf bound_ctrl:1
	v_mov_b32_dpp v100, v98 row_mirror row_mask:0xf bank_mask:0xf bound_ctrl:1
	v_pk_add_f32 v[98:99], v[98:99], v[100:101]
	s_nop 0
	v_pk_add_f32 v[100:101], v[98:99], s[2:3] op_sel_hi:[1,0]
	v_cndmask_b32_e64 v99, v133, v131, s[44:45]
	v_mul_f32_e32 v98, 0x4b800000, v101
	v_cmp_gt_f32_e32 vcc, s72, v101
	v_mad_u64_u32 v[102:103], s[0:1], v99, s14, v[0:1]
	s_nop 0
	v_cndmask_b32_e32 v98, v101, v98, vcc
	v_rsq_f32_e32 v98, v98
	v_mul_f32_e32 v101, 0x4b800000, v100
	v_and_b32_e32 v133, 0xffff0000, v54
	v_mul_f32_e32 v99, 0x45800000, v98
	v_cndmask_b32_e32 v98, v98, v99, vcc
	v_cmp_gt_f32_e32 vcc, s72, v100
	v_pk_mul_f32 v[106:107], v[106:107], v[98:99] op_sel_hi:[1,0]
	v_pk_mul_f32 v[110:111], v[140:141], v[98:99] op_sel_hi:[1,0]
	v_cndmask_b32_e32 v100, v100, v101, vcc
	v_rsq_f32_e32 v103, v100
	v_pk_mul_f32 v[108:109], v[108:109], v[98:99] op_sel_hi:[1,0]
	v_pk_mul_f32 v[116:117], v[134:135], v[98:99] op_sel_hi:[1,0]
	v_cvt_pk_bf16_f32 v98, v106, v107
	v_cvt_pk_bf16_f32 v99, v110, v111
	v_cvt_pk_bf16_f32 v100, v108, v109
	v_cvt_pk_bf16_f32 v101, v116, v117
	ds_write_b128 v102, v[98:101]
	v_mul_f32_e32 v98, 0x45800000, v103
	v_cndmask_b32_e32 v98, v103, v98, vcc
	v_pk_mul_f32 v[100:101], v[114:115], v[98:99] op_sel_hi:[1,0]
	v_pk_mul_f32 v[104:105], v[104:105], v[98:99] op_sel_hi:[1,0]
	v_pk_mul_f32 v[106:107], v[112:113], v[98:99] op_sel_hi:[1,0]
	v_pk_mul_f32 v[108:109], v[120:121], v[98:99] op_sel_hi:[1,0]
	v_or_b32_e32 v98, 3, v168
	v_sub_u32_e32 v99, 63, v98
	v_lshlrev_b32_e32 v110, 16, v97
	v_and_b32_e32 v111, 0xffff0000, v97
	v_cndmask_b32_e64 v103, v99, v98, s[44:45]
	v_cvt_pk_bf16_f32 v98, v100, v101
	v_cvt_pk_bf16_f32 v99, v104, v105
	v_lshlrev_b32_e32 v100, 16, v85
	v_and_b32_e32 v101, 0xffff0000, v85
	s_waitcnt vmcnt(8)
	v_pk_mul_f32 v[104:105], v[76:77], v[110:111]
	v_lshlrev_b32_e32 v116, 16, v84
	v_pk_fma_f32 v[100:101], v[72:73], v[100:101], v[104:105]
	v_lshlrev_b32_e32 v104, 16, v93
	v_and_b32_e32 v105, 0xffff0000, v93
	s_waitcnt vmcnt(6)
	v_pk_fma_f32 v[112:113], v[80:81], v[104:105], v[100:101]
	v_and_b32_e32 v117, 0xffff0000, v84
	v_mul_f32_e32 v85, 0xbfb8aa3b, v112
	v_exp_f32_e32 v85, v85
	v_mul_f32_e32 v93, 0xbfb8aa3b, v113
	v_exp_f32_e32 v93, v93
	v_lshlrev_b32_e32 v84, 16, v96
	v_add_f32_e32 v85, 1.0, v85
	v_rcp_f32_e32 v114, v85
	v_and_b32_e32 v85, 0xffff0000, v96
	v_cvt_pk_bf16_f32 v100, v106, v107
	v_add_f32_e32 v97, 1.0, v93
	v_lshlrev_b32_e32 v106, 16, v92
	v_and_b32_e32 v107, 0xffff0000, v92
	v_pk_mul_f32 v[92:93], v[74:75], v[84:85]
	v_rcp_f32_e32 v115, v97
	v_pk_fma_f32 v[92:93], v[70:71], v[116:117], v[92:93]
	v_lshlrev_b32_e32 v116, 16, v90
	v_pk_fma_f32 v[92:93], v[78:79], v[106:107], v[92:93]
	v_pk_mul_f32 v[120:121], v[112:113], v[114:115]
	v_mul_f32_e32 v96, 0xbfb8aa3b, v92
	v_mul_f32_e32 v101, 0xbfb8aa3b, v93
	v_exp_f32_e32 v96, v96
	v_exp_f32_e32 v101, v101
	v_lshlrev_b32_e32 v114, 16, v82
	v_and_b32_e32 v115, 0xffff0000, v82
	v_add_f32_e32 v96, 1.0, v96
	v_add_f32_e32 v97, 1.0, v101
	v_rcp_f32_e32 v96, v96
	v_rcp_f32_e32 v97, v97
	v_cvt_pk_bf16_f32 v101, v108, v109
	v_lshlrev_b32_e32 v108, 16, v91
	v_and_b32_e32 v109, 0xffff0000, v91
	v_pk_mul_f32 v[124:125], v[92:93], v[96:97]
	v_lshlrev_b32_e32 v96, 16, v95
	v_and_b32_e32 v97, 0xffff0000, v95
	v_lshlrev_b32_e32 v92, 16, v83
	v_and_b32_e32 v93, 0xffff0000, v83
	v_pk_mul_f32 v[112:113], v[64:65], v[96:97]
	v_lshlrev_b32_e32 v82, 16, v94
	v_pk_fma_f32 v[92:93], v[60:61], v[92:93], v[112:113]
	v_and_b32_e32 v117, 0xffff0000, v90
	v_pk_fma_f32 v[92:93], v[68:69], v[108:109], v[92:93]
	v_pk_mul_f32 v[136:137], v[64:65], v[108:109]
	v_mul_f32_e32 v83, 0xbfb8aa3b, v92
	v_exp_f32_e32 v83, v83
	v_mul_f32_e32 v91, 0xbfb8aa3b, v93
	v_exp_f32_e32 v91, v91
	v_pk_fma_f32 v[96:97], v[60:61], v[96:97], v[136:137]
	v_add_f32_e32 v83, 1.0, v83
	v_rcp_f32_e32 v112, v83
	v_add_f32_e32 v83, 1.0, v91
	v_rcp_f32_e32 v113, v83
	v_and_b32_e32 v83, 0xffff0000, v94
	v_pk_mul_f32 v[90:91], v[62:63], v[82:83]
	v_pk_mul_f32 v[126:127], v[124:125], v[124:125]
	v_pk_fma_f32 v[90:91], v[58:59], v[114:115], v[90:91]
	v_pk_mul_f32 v[122:123], v[120:121], v[120:121]
	v_pk_fma_f32 v[90:91], v[66:67], v[116:117], v[90:91]
	s_nop 0
	v_mul_f32_e32 v94, 0xbfb8aa3b, v90
	v_exp_f32_e32 v114, v94
	v_mul_f32_e32 v94, 0xbfb8aa3b, v91
	v_exp_f32_e32 v115, v94
	v_pk_mul_f32 v[94:95], v[92:93], v[112:113]
	v_pk_mul_f32 v[112:113], v[76:77], v[104:105]
	v_add_f32_e32 v92, 1.0, v114
	v_pk_fma_f32 v[110:111], v[72:73], v[110:111], v[112:113]
	v_add_f32_e32 v93, 1.0, v115
	v_pk_fma_f32 v[110:111], v[80:81], v[118:119], v[110:111]
	v_lshlrev_b32_e32 v114, 16, v88
	v_mul_f32_e32 v89, 0xbfb8aa3b, v110
	v_exp_f32_e32 v89, v89
	v_mul_f32_e32 v112, 0xbfb8aa3b, v111
	v_exp_f32_e32 v113, v112
	v_and_b32_e32 v115, 0xffff0000, v88
	v_add_f32_e32 v89, 1.0, v89
	v_rcp_f32_e32 v112, v89
	v_add_f32_e32 v89, 1.0, v113
	v_rcp_f32_e32 v113, v89
	v_pk_mul_f32 v[88:89], v[74:75], v[106:107]
	v_rcp_f32_e32 v92, v92
	v_pk_fma_f32 v[84:85], v[70:71], v[84:85], v[88:89]
	v_pk_mul_f32 v[134:135], v[110:111], v[112:113]
	v_pk_fma_f32 v[84:85], v[78:79], v[114:115], v[84:85]
	v_lshlrev_b32_e32 v112, 16, v87
	v_mul_f32_e32 v88, 0xbfb8aa3b, v84
	v_exp_f32_e32 v110, v88
	v_mul_f32_e32 v88, 0xbfb8aa3b, v85
	v_exp_f32_e32 v111, v88
	v_and_b32_e32 v113, 0xffff0000, v87
	v_pk_fma_f32 v[96:97], v[68:69], v[112:113], v[96:97]
	v_add_f32_e32 v110, 1.0, v110
	v_add_f32_e32 v111, 1.0, v111
	v_mul_f32_e32 v87, 0xbfb8aa3b, v96
	v_rcp_f32_e32 v110, v110
	v_rcp_f32_e32 v111, v111
	v_exp_f32_e32 v87, v87
	v_mul_f32_e32 v131, 0xbfb8aa3b, v97
	v_exp_f32_e32 v131, v131
	v_pk_mul_f32 v[136:137], v[84:85], v[110:111]
	v_add_f32_e32 v84, 1.0, v87
	v_lshlrev_b32_e32 v110, 16, v86
	v_and_b32_e32 v111, 0xffff0000, v86
	v_pk_mul_f32 v[86:87], v[62:63], v[116:117]
	v_rcp_f32_e32 v93, v93
	v_pk_fma_f32 v[82:83], v[58:59], v[82:83], v[86:87]
	v_add_f32_e32 v85, 1.0, v131
	v_pk_fma_f32 v[82:83], v[66:67], v[110:111], v[82:83]
	v_rcp_f32_e32 v84, v84
	v_mul_f32_e32 v86, 0xbfb8aa3b, v82
	v_mul_f32_e32 v87, 0xbfb8aa3b, v83
	v_exp_f32_e32 v86, v86
	v_exp_f32_e32 v87, v87
	v_rcp_f32_e32 v85, v85
	v_pk_mul_f32 v[90:91], v[90:91], v[92:93]
	v_add_f32_e32 v86, 1.0, v86
	v_add_f32_e32 v87, 1.0, v87
	v_rcp_f32_e32 v86, v86
	v_rcp_f32_e32 v87, v87
	v_pk_mul_f32 v[92:93], v[90:91], v[90:91]
	v_pk_mul_f32 v[140:141], v[96:97], v[84:85]
	v_pk_mul_f32 v[128:129], v[94:95], v[94:95]
	v_pk_mul_f32 v[86:87], v[82:83], v[86:87]
	v_pk_mul_f32 v[84:85], v[140:141], v[140:141]
	v_pk_mul_f32 v[82:83], v[86:87], v[86:87]
	v_mov_b32_e32 v97, v92
	v_mov_b32_e32 v96, v82
	v_mov_b32_e32 v92, v83
	v_pk_add_f32 v[82:83], v[96:97], v[92:93]
	v_mov_b32_e32 v92, v84
	v_mov_b32_e32 v93, v128
	v_pk_mul_f32 v[138:139], v[136:137], v[136:137]
	v_pk_add_f32 v[82:83], v[92:93], v[82:83]
	v_mov_b32_e32 v128, v85
	v_pk_add_f32 v[82:83], v[128:129], v[82:83]
	v_mov_b32_e32 v84, v138
	v_mov_b32_e32 v85, v126
	v_pk_mul_f32 v[88:89], v[134:135], v[134:135]
	v_pk_add_f32 v[82:83], v[84:85], v[82:83]
	v_mov_b32_e32 v126, v139
	v_pk_add_f32 v[82:83], v[126:127], v[82:83]
	v_mov_b32_e32 v84, v88
	v_mov_b32_e32 v85, v122
	v_pk_add_f32 v[82:83], v[84:85], v[82:83]
	v_mov_b32_e32 v122, v89
	v_pk_add_f32 v[82:83], v[122:123], v[82:83]
	v_mad_u64_u32 v[96:97], s[0:1], v103, s14, v[0:1]
	s_nop 0
	v_mov_b32_dpp v85, v83 quad_perm:[1,0,3,2] row_mask:0xf bank_mask:0xf bound_ctrl:1
	v_mov_b32_dpp v84, v82 quad_perm:[1,0,3,2] row_mask:0xf bank_mask:0xf bound_ctrl:1
	v_pk_add_f32 v[82:83], v[82:83], v[84:85]
	ds_write_b128 v96, v[98:101]
	v_pk_mul_f32 v[126:127], v[64:65], v[112:113]
	v_mov_b32_dpp v85, v83 quad_perm:[2,3,0,1] row_mask:0xf bank_mask:0xf bound_ctrl:1
	v_mov_b32_dpp v84, v82 quad_perm:[2,3,0,1] row_mask:0xf bank_mask:0xf bound_ctrl:1
	v_pk_add_f32 v[82:83], v[82:83], v[84:85]
	v_pk_fma_f32 v[108:109], v[60:61], v[108:109], v[126:127]
	s_movk_i32 s0, 0x48
	v_mov_b32_dpp v85, v83 row_half_mirror row_mask:0xf bank_mask:0xf bound_ctrl:1
	v_mov_b32_dpp v84, v82 row_half_mirror row_mask:0xf bank_mask:0xf bound_ctrl:1
	v_pk_add_f32 v[82:83], v[82:83], v[84:85]
	s_nop 1
	v_mov_b32_dpp v85, v83 row_mirror row_mask:0xf bank_mask:0xf bound_ctrl:1
	v_mov_b32_dpp v84, v82 row_mirror row_mask:0xf bank_mask:0xf bound_ctrl:1
	v_pk_add_f32 v[82:83], v[82:83], v[84:85]
	s_nop 0
	v_pk_add_f32 v[122:123], v[82:83], s[2:3] op_sel_hi:[1,0]
	s_nop 0
	v_mul_f32_e32 v82, 0x4b800000, v123
	v_cmp_gt_f32_e32 vcc, s72, v123
	s_nop 1
	v_cndmask_b32_e32 v82, v123, v82, vcc
	v_rsq_f32_e32 v82, v82
	s_nop 0
	v_mul_f32_e32 v0, 0x45800000, v82
	v_cndmask_b32_e32 v0, v82, v0, vcc
	v_pk_mul_f32 v[92:93], v[90:91], v[0:1] op_sel_hi:[1,0]
	v_pk_mul_f32 v[88:89], v[94:95], v[0:1] op_sel_hi:[1,0]
	v_pk_mul_f32 v[84:85], v[124:125], v[0:1] op_sel_hi:[1,0]
	v_pk_mul_f32 v[82:83], v[120:121], v[0:1] op_sel_hi:[1,0]
	v_mul_f32_e32 v0, 0x4b800000, v122
	v_cmp_gt_f32_e32 vcc, s72, v122
	v_cvt_pk_bf16_f32 v98, v92, v93
	v_cvt_pk_bf16_f32 v99, v88, v89
	v_cndmask_b32_e32 v0, v122, v0, vcc
	v_rsq_f32_e32 v0, v0
	v_cvt_pk_bf16_f32 v100, v84, v85
	v_cvt_pk_bf16_f32 v101, v82, v83
	ds_write_b128 v132, v[98:101] offset:17408
	v_pk_mul_f32 v[100:101], v[76:77], v[118:119]
	v_mul_f32_e32 v90, 0x45800000, v0
	v_pk_fma_f32 v[100:101], v[72:73], v[104:105], v[100:101]
	v_lshlrev_b32_e32 v120, 16, v57
	v_and_b32_e32 v121, 0xffff0000, v57
	v_cndmask_b32_e32 v0, v0, v90, vcc
	v_pk_fma_f32 v[100:101], v[80:81], v[120:121], v[100:101]
	v_pk_mul_f32 v[98:99], v[86:87], v[0:1] op_sel_hi:[1,0]
	v_pk_mul_f32 v[94:95], v[140:141], v[0:1] op_sel_hi:[1,0]
	v_pk_mul_f32 v[90:91], v[136:137], v[0:1] op_sel_hi:[1,0]
	v_pk_mul_f32 v[86:87], v[134:135], v[0:1] op_sel_hi:[1,0]
	v_mul_f32_e32 v0, 0xbfb8aa3b, v100
	v_exp_f32_e32 v0, v0
	v_mul_f32_e32 v57, 0xbfb8aa3b, v101
	v_exp_f32_e32 v57, v57
	v_lshlrev_b32_e32 v124, 16, v56
	v_add_f32_e32 v0, 1.0, v0
	v_rcp_f32_e32 v122, v0
	v_add_f32_e32 v0, 1.0, v57
	v_and_b32_e32 v125, 0xffff0000, v56
	v_pk_mul_f32 v[56:57], v[74:75], v[114:115]
	v_rcp_f32_e32 v123, v0
	v_pk_fma_f32 v[56:57], v[70:71], v[106:107], v[56:57]
	v_lshlrev_b32_e32 v132, 16, v54
	v_pk_fma_f32 v[56:57], v[78:79], v[124:125], v[56:57]
	v_pk_mul_f32 v[76:77], v[76:77], v[120:121]
	v_mul_f32_e32 v97, 0xbfb8aa3b, v56
	v_exp_f32_e32 v97, v97
	v_mul_f32_e32 v103, 0xbfb8aa3b, v57
	v_exp_f32_e32 v103, v103
	v_pk_fma_f32 v[72:73], v[72:73], v[118:119], v[76:77]
	v_add_f32_e32 v0, 1.0, v97
	v_rcp_f32_e32 v106, v0
	v_add_f32_e32 v0, 1.0, v103
	v_rcp_f32_e32 v107, v0
	v_lshlrev_b32_e32 v76, 16, v53
	v_and_b32_e32 v77, 0xffff0000, v53
	v_pk_fma_f32 v[72:73], v[80:81], v[76:77], v[72:73]
	v_pk_mul_f32 v[56:57], v[56:57], v[106:107]
	v_lshlrev_b32_e32 v106, 16, v55
	v_and_b32_e32 v107, 0xffff0000, v55
	v_pk_fma_f32 v[108:109], v[68:69], v[106:107], v[108:109]
	v_mul_f32_e32 v53, 0xbfb8aa3b, v72
	v_mul_f32_e32 v0, 0xbfb8aa3b, v108
	v_exp_f32_e32 v0, v0
	v_mul_f32_e32 v55, 0xbfb8aa3b, v109
	v_exp_f32_e32 v55, v55
	v_exp_f32_e32 v53, v53
	v_add_f32_e32 v0, 1.0, v0
	v_rcp_f32_e32 v128, v0
	v_add_f32_e32 v0, 1.0, v55
	v_pk_mul_f32 v[54:55], v[62:63], v[110:111]
	v_rcp_f32_e32 v129, v0
	v_pk_fma_f32 v[54:55], v[58:59], v[116:117], v[54:55]
	v_mul_f32_e32 v76, 0xbfb8aa3b, v73
	v_pk_fma_f32 v[54:55], v[66:67], v[132:133], v[54:55]
	v_exp_f32_e32 v77, v76
	v_mul_f32_e32 v0, 0xbfb8aa3b, v54
	v_exp_f32_e32 v0, v0
	v_mul_f32_e32 v97, 0xbfb8aa3b, v55
	v_exp_f32_e32 v97, v97
	v_pk_mul_f32 v[64:65], v[64:65], v[106:107]
	v_add_f32_e32 v0, 1.0, v0
	v_rcp_f32_e32 v116, v0
	v_add_f32_e32 v0, 1.0, v97
	v_rcp_f32_e32 v117, v0
	v_add_f32_e32 v0, 1.0, v53
	v_rcp_f32_e32 v76, v0
	v_add_f32_e32 v0, 1.0, v77
	v_rcp_f32_e32 v77, v0
	v_pk_fma_f32 v[60:61], v[60:61], v[112:113], v[64:65]
	v_pk_mul_f32 v[54:55], v[54:55], v[116:117]
	v_pk_mul_f32 v[108:109], v[108:109], v[128:129]
	v_pk_mul_f32 v[72:73], v[72:73], v[76:77]
	v_lshlrev_b32_e32 v76, 16, v52
	v_and_b32_e32 v77, 0xffff0000, v52
	v_pk_mul_f32 v[52:53], v[74:75], v[124:125]
	v_pk_mul_f32 v[116:117], v[54:55], v[54:55]
	v_pk_fma_f32 v[52:53], v[70:71], v[114:115], v[52:53]
	v_pk_mul_f32 v[80:81], v[108:109], v[108:109]
	v_pk_fma_f32 v[52:53], v[78:79], v[76:77], v[52:53]
	v_lshlrev_b32_e32 v76, 16, v51
	v_mul_f32_e32 v0, 0xbfb8aa3b, v52
	v_exp_f32_e32 v0, v0
	v_mul_f32_e32 v70, 0xbfb8aa3b, v53
	v_exp_f32_e32 v75, v70
	v_and_b32_e32 v77, 0xffff0000, v51
	v_add_f32_e32 v0, 1.0, v0
	v_rcp_f32_e32 v74, v0
	v_add_f32_e32 v0, 1.0, v75
	v_pk_fma_f32 v[60:61], v[68:69], v[76:77], v[60:61]
	v_rcp_f32_e32 v75, v0
	v_mul_f32_e32 v0, 0xbfb8aa3b, v60
	v_exp_f32_e32 v0, v0
	v_mul_f32_e32 v51, 0xbfb8aa3b, v61
	v_exp_f32_e32 v51, v51
	v_pk_mul_f32 v[64:65], v[52:53], v[74:75]
	v_add_f32_e32 v0, 1.0, v0
	v_rcp_f32_e32 v52, v0
	v_add_f32_e32 v0, 1.0, v51
	v_lshlrev_b32_e32 v68, 16, v50
	v_and_b32_e32 v69, 0xffff0000, v50
	v_pk_mul_f32 v[50:51], v[62:63], v[132:133]
	v_pk_mul_f32 v[126:127], v[56:57], v[56:57]
	v_pk_fma_f32 v[50:51], v[58:59], v[110:111], v[50:51]
	v_pk_mul_f32 v[62:63], v[64:65], v[64:65]
	v_pk_fma_f32 v[50:51], v[66:67], v[68:69], v[50:51]
	v_mov_b32_e32 v67, v116
	v_mul_f32_e32 v53, 0xbfb8aa3b, v50
	v_exp_f32_e32 v58, v53
	v_mul_f32_e32 v53, 0xbfb8aa3b, v51
	v_exp_f32_e32 v59, v53
	v_rcp_f32_e32 v53, v0
	v_add_f32_e32 v0, 1.0, v58
	v_rcp_f32_e32 v58, v0
	v_add_f32_e32 v0, 1.0, v59
	v_rcp_f32_e32 v59, v0
	v_pk_mul_f32 v[60:61], v[60:61], v[52:53]
	v_pk_mul_f32 v[100:101], v[100:101], v[122:123]
	v_pk_mul_f32 v[52:53], v[60:61], v[60:61]
	v_pk_mul_f32 v[58:59], v[50:51], v[58:59]
	v_pk_mul_f32 v[122:123], v[100:101], v[100:101]
	v_pk_mul_f32 v[50:51], v[58:59], v[58:59]
	v_pk_mul_f32 v[70:71], v[72:73], v[72:73]
	v_mov_b32_e32 v66, v50
	v_mov_b32_e32 v116, v51
	v_pk_add_f32 v[50:51], v[66:67], v[116:117]
	v_mov_b32_e32 v66, v52
	v_mov_b32_e32 v67, v80
	v_pk_add_f32 v[50:51], v[66:67], v[50:51]
	v_mov_b32_e32 v80, v53
	v_pk_add_f32 v[50:51], v[80:81], v[50:51]
	v_mov_b32_e32 v52, v62
	v_mov_b32_e32 v53, v126
	v_pk_add_f32 v[50:51], v[52:53], v[50:51]
	v_mov_b32_e32 v126, v63
	v_pk_add_f32 v[50:51], v[126:127], v[50:51]
	v_mov_b32_e32 v52, v70
	v_mov_b32_e32 v53, v122
	v_pk_add_f32 v[50:51], v[52:53], v[50:51]
	v_mov_b32_e32 v122, v71
	v_pk_add_f32 v[50:51], v[122:123], v[50:51]
	v_cvt_pk_bf16_f32 v104, v98, v99
	v_cvt_pk_bf16_f32 v105, v94, v95
	v_mov_b32_dpp v53, v51 quad_perm:[1,0,3,2] row_mask:0xf bank_mask:0xf bound_ctrl:1
	v_mov_b32_dpp v52, v50 quad_perm:[1,0,3,2] row_mask:0xf bank_mask:0xf bound_ctrl:1
	v_pk_add_f32 v[50:51], v[50:51], v[52:53]
	v_cvt_pk_bf16_f32 v106, v90, v91
	v_cvt_pk_bf16_f32 v107, v86, v87
	v_mov_b32_dpp v53, v51 quad_perm:[2,3,0,1] row_mask:0xf bank_mask:0xf bound_ctrl:1
	v_mov_b32_dpp v52, v50 quad_perm:[2,3,0,1] row_mask:0xf bank_mask:0xf bound_ctrl:1
	v_pk_add_f32 v[50:51], v[50:51], v[52:53]
	ds_write_b128 v130, v[104:107] offset:17408
	s_nop 0
	v_mov_b32_dpp v53, v51 row_half_mirror row_mask:0xf bank_mask:0xf bound_ctrl:1
	v_mov_b32_dpp v52, v50 row_half_mirror row_mask:0xf bank_mask:0xf bound_ctrl:1
	v_pk_add_f32 v[50:51], v[50:51], v[52:53]
	s_nop 1
	v_mov_b32_dpp v53, v51 row_mirror row_mask:0xf bank_mask:0xf bound_ctrl:1
	v_mov_b32_dpp v52, v50 row_mirror row_mask:0xf bank_mask:0xf bound_ctrl:1
	v_pk_add_f32 v[50:51], v[50:51], v[52:53]
	s_nop 0
	v_pk_add_f32 v[52:53], v[50:51], s[2:3] op_sel_hi:[1,0]
	s_nop 0
	v_mul_f32_e32 v0, 0x4b800000, v53
	v_cmp_gt_f32_e32 vcc, s72, v53
	s_nop 1
	v_cndmask_b32_e32 v0, v53, v0, vcc
	v_rsq_f32_e32 v0, v0
	s_nop 0
	v_mul_f32_e32 v50, 0x45800000, v0
	v_cndmask_b32_e32 v0, v0, v50, vcc
	v_pk_mul_f32 v[54:55], v[54:55], v[0:1] op_sel_hi:[1,0]
	v_pk_mul_f32 v[62:63], v[108:109], v[0:1] op_sel_hi:[1,0]
	v_pk_mul_f32 v[56:57], v[56:57], v[0:1] op_sel_hi:[1,0]
	v_pk_mul_f32 v[66:67], v[100:101], v[0:1] op_sel_hi:[1,0]
	v_mul_f32_e32 v0, 0x4b800000, v52
	v_cmp_gt_f32_e32 vcc, s72, v52
	v_cvt_pk_bf16_f32 v50, v54, v55
	v_cvt_pk_bf16_f32 v51, v62, v63
	v_cndmask_b32_e32 v0, v52, v0, vcc
	v_rsq_f32_e32 v0, v0
	v_cvt_pk_bf16_f32 v52, v56, v57
	v_cvt_pk_bf16_f32 v53, v66, v67
	ds_write_b128 v102, v[50:53] offset:17408
	v_mul_f32_e32 v50, 0x45800000, v0
	v_cndmask_b32_e32 v0, v0, v50, vcc
	v_pk_mul_f32 v[58:59], v[58:59], v[0:1] op_sel_hi:[1,0]
	v_pk_mul_f32 v[60:61], v[60:61], v[0:1] op_sel_hi:[1,0]
	v_pk_mul_f32 v[64:65], v[64:65], v[0:1] op_sel_hi:[1,0]
	v_pk_mul_f32 v[68:69], v[72:73], v[0:1] op_sel_hi:[1,0]
	v_cvt_pk_bf16_f32 v50, v58, v59
	v_cvt_pk_bf16_f32 v51, v60, v61
	v_cvt_pk_bf16_f32 v52, v64, v65
	v_cvt_pk_bf16_f32 v53, v68, v69
	ds_write_b128 v96, v[50:53] offset:17408
	v_cndmask_b32_e64 v0, v58, v92, s[44:45]
	v_cndmask_b32_e64 v50, v54, v98, s[44:45]
	v_cndmask_b32_e64 v51, v98, v54, s[44:45]
	v_cndmask_b32_e64 v52, v92, v58, s[44:45]
	v_cvt_pk_bf16_f32 v50, v0, v50
	v_mad_u32_u24 v0, v167, s0, v169
	v_cvt_pk_bf16_f32 v51, v51, v52
	v_lshl_add_u32 v0, v0, 1, v146
	v_cndmask_b32_e64 v52, v59, v93, s[44:45]
	v_cndmask_b32_e64 v53, v55, v99, s[44:45]
	v_cndmask_b32_e64 v54, v99, v55, s[44:45]
	v_cndmask_b32_e64 v55, v93, v59, s[44:45]
	v_cvt_pk_bf16_f32 v52, v52, v53
	v_cvt_pk_bf16_f32 v53, v54, v55
	v_add_u32_e32 v70, 0x8800, v0
	ds_write2_b64 v70, v[50:51], v[52:53] offset1:18
	v_cndmask_b32_e64 v50, v60, v88, s[44:45]
	v_cndmask_b32_e64 v51, v62, v94, s[44:45]
	v_cndmask_b32_e64 v52, v94, v62, s[44:45]
	v_cndmask_b32_e64 v53, v88, v60, s[44:45]
	v_cvt_pk_bf16_f32 v50, v50, v51
	v_cvt_pk_bf16_f32 v51, v52, v53
	v_cndmask_b32_e64 v52, v61, v89, s[44:45]
	v_cndmask_b32_e64 v53, v63, v95, s[44:45]
	v_cndmask_b32_e64 v54, v95, v63, s[44:45]
	v_cndmask_b32_e64 v55, v89, v61, s[44:45]
	v_cvt_pk_bf16_f32 v52, v52, v53
	v_cvt_pk_bf16_f32 v53, v54, v55
	ds_write2_b64 v70, v[50:51], v[52:53] offset0:36 offset1:54
	v_cndmask_b32_e64 v50, v64, v84, s[44:45]
	v_cndmask_b32_e64 v51, v56, v90, s[44:45]
	v_cndmask_b32_e64 v52, v90, v56, s[44:45]
	v_cndmask_b32_e64 v53, v84, v64, s[44:45]
	v_cvt_pk_bf16_f32 v50, v50, v51
	v_cvt_pk_bf16_f32 v51, v52, v53
	v_cndmask_b32_e64 v52, v65, v85, s[44:45]
	v_cndmask_b32_e64 v53, v57, v91, s[44:45]
	v_cndmask_b32_e64 v54, v91, v57, s[44:45]
	v_cndmask_b32_e64 v55, v85, v65, s[44:45]
	v_cvt_pk_bf16_f32 v52, v52, v53
	v_cvt_pk_bf16_f32 v53, v54, v55
	v_lshlrev_b32_e32 v54, 16, v10
	v_lshlrev_b32_e32 v56, 16, v6
	v_mov_b32_e32 v57, v54
	v_lshlrev_b32_e32 v55, 16, v2
	v_mov_b32_e32 v58, v56
	s_waitcnt vmcnt(3)
	v_pk_mul_f32 v[56:57], v[42:43], v[56:57] op_sel_hi:[0,1]
	ds_write2_b64 v70, v[50:51], v[52:53] offset0:72 offset1:90
	v_cndmask_b32_e64 v50, v68, v82, s[44:45]
	v_cndmask_b32_e64 v51, v66, v86, s[44:45]
	v_cndmask_b32_e64 v52, v86, v66, s[44:45]
	v_cndmask_b32_e64 v53, v82, v68, s[44:45]
	v_lshlrev_b32_e32 v59, 16, v18
	v_pk_fma_f32 v[54:55], v[38:39], v[54:55], v[56:57] op_sel_hi:[0,1,1]
	v_cvt_pk_bf16_f32 v50, v50, v51
	v_cvt_pk_bf16_f32 v51, v52, v53
	v_cndmask_b32_e64 v52, v69, v83, s[44:45]
	v_cndmask_b32_e64 v53, v67, v87, s[44:45]
	s_waitcnt vmcnt(1)
	v_pk_fma_f32 v[54:55], v[46:47], v[58:59], v[54:55] op_sel:[0,1,0] op_sel_hi:[0,0,1]
	v_cvt_pk_bf16_f32 v52, v52, v53
	v_mul_f32_e32 v53, 0xbfb8aa3b, v55
	v_exp_f32_e32 v53, v53
	v_mul_f32_e32 v56, 0xbfb8aa3b, v54
	v_exp_f32_e32 v56, v56
	v_lshlrev_b32_e32 v61, 16, v14
	v_mov_b32_e32 v60, v59
	v_add_f32_e32 v53, 1.0, v53
	v_rcp_f32_e32 v63, v53
	v_add_f32_e32 v53, 1.0, v56
	v_mov_b32_e32 v56, v61
	v_pk_mul_f32 v[60:61], v[42:43], v[60:61] op_sel_hi:[0,1]
	v_lshlrev_b32_e32 v57, 16, v22
	v_pk_fma_f32 v[58:59], v[38:39], v[58:59], v[60:61] op_sel_hi:[0,1,1]
	v_pk_fma_f32 v[56:57], v[46:47], v[56:57], v[58:59] op_sel_hi:[0,1,1]
	v_mul_f32_e32 v58, 0xbfb8aa3b, v56
	v_exp_f32_e32 v58, v58
	v_mul_f32_e32 v59, 0xbfb8aa3b, v57
	v_exp_f32_e32 v59, v59
	v_rcp_f32_e32 v62, v53
	v_add_f32_e32 v53, 1.0, v58
	v_rcp_f32_e32 v58, v53
	v_add_f32_e32 v53, 1.0, v59
	v_rcp_f32_e32 v59, v53
	v_cndmask_b32_e64 v64, v87, v67, s[44:45]
	v_cndmask_b32_e64 v65, v83, v69, s[44:45]
	v_cvt_pk_bf16_f32 v53, v64, v65
	ds_write2_b64 v70, v[50:51], v[52:53] offset0:108 offset1:126
	v_pk_mul_f32 v[50:51], v[54:55], v[62:63]
	v_pk_mul_f32 v[52:53], v[56:57], v[58:59]
	v_and_b32_e32 v55, 0xffff0000, v18
	v_cndmask_b32_e64 v61, v52, v50, s[44:45]
	v_cndmask_b32_e64 v63, v50, v52, s[44:45]
	v_and_b32_e32 v50, 0xffff0000, v10
	v_cndmask_b32_e64 v60, v53, v51, s[44:45]
	v_cndmask_b32_e64 v62, v51, v53, s[44:45]
	v_and_b32_e32 v52, 0xffff0000, v6
	v_mov_b32_e32 v53, v50
	v_and_b32_e32 v51, 0xffff0000, v2
	v_mov_b32_e32 v54, v52
	v_pk_mul_f32 v[52:53], v[42:43], v[52:53] op_sel:[1,0]
	v_and_b32_e32 v57, 0xffff0000, v14
	v_pk_fma_f32 v[50:51], v[38:39], v[50:51], v[52:53] op_sel:[1,0,0]
	v_mov_b32_e32 v56, v55
	v_pk_fma_f32 v[50:51], v[46:47], v[54:55], v[50:51] op_sel:[1,1,0] op_sel_hi:[1,0,1]
	v_pk_mul_f32 v[42:43], v[42:43], v[56:57] op_sel:[1,0]
	v_mul_f32_e32 v2, 0xbfb8aa3b, v51
	v_exp_f32_e32 v2, v2
	v_mul_f32_e32 v6, 0xbfb8aa3b, v50
	v_exp_f32_e32 v6, v6
	v_and_b32_e32 v53, 0xffff0000, v22
	v_mov_b32_e32 v52, v57
	v_pk_fma_f32 v[38:39], v[38:39], v[54:55], v[42:43] op_sel:[1,0,0]
	v_add_f32_e32 v2, 1.0, v2
	v_pk_fma_f32 v[38:39], v[46:47], v[52:53], v[38:39] op_sel:[1,0,0]
	v_rcp_f32_e32 v59, v2
	v_add_f32_e32 v2, 1.0, v6
	v_mul_f32_e32 v6, 0xbfb8aa3b, v38
	v_exp_f32_e32 v6, v6
	v_mul_f32_e32 v10, 0xbfb8aa3b, v39
	v_exp_f32_e32 v10, v10
	v_rcp_f32_e32 v58, v2
	v_add_f32_e32 v2, 1.0, v6
	v_rcp_f32_e32 v42, v2
	v_add_f32_e32 v2, 1.0, v10
	v_rcp_f32_e32 v43, v2
	v_pk_mul_f32 v[50:51], v[50:51], v[58:59]
	v_lshlrev_b32_e32 v53, 16, v19
	v_lshlrev_b32_e32 v55, 16, v15
	v_pk_mul_f32 v[38:39], v[38:39], v[42:43]
	v_lshlrev_b32_e32 v42, 16, v11
	v_cndmask_b32_e64 v2, v39, v51, s[44:45]
	v_cndmask_b32_e64 v6, v38, v50, s[44:45]
	v_cndmask_b32_e64 v10, v51, v39, s[44:45]
	v_cndmask_b32_e64 v14, v50, v38, s[44:45]
	v_lshlrev_b32_e32 v50, 16, v7
	v_mov_b32_e32 v51, v42
	v_lshlrev_b32_e32 v43, 16, v3
	v_mov_b32_e32 v52, v50
	v_pk_mul_f32 v[50:51], v[44:45], v[50:51] op_sel_hi:[0,1]
	v_pk_fma_f32 v[42:43], v[40:41], v[42:43], v[50:51] op_sel_hi:[0,1,1]
	v_pk_fma_f32 v[42:43], v[48:49], v[52:53], v[42:43] op_sel:[0,1,0] op_sel_hi:[0,0,1]
	v_cvt_pk_bf16_f32 v38, v2, v6
	v_mul_f32_e32 v2, 0xbfb8aa3b, v43
	v_exp_f32_e32 v2, v2
	v_mul_f32_e32 v6, 0xbfb8aa3b, v42
	v_exp_f32_e32 v6, v6
	v_mov_b32_e32 v54, v53
	v_mov_b32_e32 v50, v55
	v_pk_mul_f32 v[54:55], v[44:45], v[54:55] op_sel_hi:[0,1]
	v_lshlrev_b32_e32 v51, 16, v23
	v_pk_fma_f32 v[52:53], v[40:41], v[52:53], v[54:55] op_sel_hi:[0,1,1]
	v_add_f32_e32 v2, 1.0, v2
	v_pk_fma_f32 v[50:51], v[48:49], v[50:51], v[52:53] op_sel_hi:[0,1,1]
	v_rcp_f32_e32 v57, v2
	v_add_f32_e32 v2, 1.0, v6
	v_mul_f32_e32 v6, 0xbfb8aa3b, v50
	v_cvt_pk_bf16_f32 v39, v14, v10
	v_exp_f32_e32 v6, v6
	v_mul_f32_e32 v10, 0xbfb8aa3b, v51
	v_exp_f32_e32 v10, v10
	v_rcp_f32_e32 v56, v2
	v_add_f32_e32 v2, 1.0, v6
	v_rcp_f32_e32 v52, v2
	v_add_f32_e32 v2, 1.0, v10
	v_rcp_f32_e32 v53, v2
	v_and_b32_e32 v2, 0xffff0000, v11
	v_and_b32_e32 v6, 0xffff0000, v7
	v_mov_b32_e32 v7, v2
	v_mov_b32_e32 v18, v45
	v_add_u32_e32 v40, 0xd000, v0
	v_and_b32_e32 v3, 0xffff0000, v3
	v_mov_b32_e32 v10, v6
	v_mov_b32_e32 v0, v41
	v_pk_mul_f32 v[6:7], v[18:19], v[6:7] op_sel_hi:[0,1]
	v_and_b32_e32 v11, 0xffff0000, v19
	v_pk_fma_f32 v[2:3], v[0:1], v[2:3], v[6:7] op_sel_hi:[0,1,1]
	v_mov_b32_e32 v22, v49
	v_pk_fma_f32 v[2:3], v[22:23], v[10:11], v[2:3] op_sel:[0,1,0] op_sel_hi:[0,0,1]
	v_mul_f32_e32 v6, 0xbfb8aa3b, v3
	v_exp_f32_e32 v19, v6
	v_mul_f32_e32 v6, 0xbfb8aa3b, v2
	v_and_b32_e32 v7, 0xffff0000, v23
	v_exp_f32_e32 v23, v6
	v_add_f32_e32 v19, 1.0, v19
	v_rcp_f32_e32 v19, v19
	v_and_b32_e32 v15, 0xffff0000, v15
	v_mov_b32_e32 v14, v11
	v_mov_b32_e32 v6, v15
	v_pk_mul_f32 v[14:15], v[18:19], v[14:15] op_sel_hi:[0,1]
	v_add_f32_e32 v23, 1.0, v23
	v_pk_fma_f32 v[10:11], v[0:1], v[10:11], v[14:15] op_sel_hi:[0,1,1]
	v_pk_fma_f32 v[6:7], v[22:23], v[6:7], v[10:11] op_sel_hi:[0,1,1]
	v_mul_f32_e32 v0, 0xbfb8aa3b, v6
	v_exp_f32_e32 v0, v0
	v_mul_f32_e32 v10, 0xbfb8aa3b, v7
	v_exp_f32_e32 v11, v10
	v_rcp_f32_e32 v18, v23
	v_add_f32_e32 v0, 1.0, v0
	v_rcp_f32_e32 v10, v0
	v_add_f32_e32 v0, 1.0, v11
	v_rcp_f32_e32 v11, v0
	v_pk_mul_f32 v[2:3], v[2:3], v[18:19]
	v_lshlrev_b32_e32 v19, 16, v20
	v_cvt_pk_bf16_f32 v46, v60, v61
	v_pk_mul_f32 v[6:7], v[6:7], v[10:11]
	v_cvt_pk_bf16_f32 v47, v63, v62
	v_cndmask_b32_e64 v0, v7, v3, s[44:45]
	v_cndmask_b32_e64 v10, v6, v2, s[44:45]
	v_cndmask_b32_e64 v41, v2, v6, s[44:45]
	v_lshlrev_b32_e32 v6, 16, v12
	v_cvt_pk_bf16_f32 v2, v0, v10
	v_lshlrev_b32_e32 v10, 16, v8
	v_mov_b32_e32 v11, v6
	v_cndmask_b32_e64 v3, v3, v7, s[44:45]
	v_lshlrev_b32_e32 v7, 16, v4
	v_mov_b32_e32 v18, v10
	v_pk_mul_f32 v[10:11], v[30:31], v[10:11] op_sel_hi:[0,1]
	v_pk_fma_f32 v[6:7], v[26:27], v[6:7], v[10:11] op_sel_hi:[0,1,1]
	s_waitcnt vmcnt(0)
	v_pk_fma_f32 v[6:7], v[34:35], v[18:19], v[6:7] op_sel:[0,1,0] op_sel_hi:[0,0,1]
	v_mul_f32_e32 v0, 0xbfb8aa3b, v7
	v_exp_f32_e32 v0, v0
	v_mul_f32_e32 v10, 0xbfb8aa3b, v6
	v_exp_f32_e32 v10, v10
	ds_write2_b64 v40, v[46:47], v[38:39] offset1:18
	v_pk_mul_f32 v[38:39], v[42:43], v[56:57]
	v_pk_mul_f32 v[42:43], v[50:51], v[52:53]
	v_lshlrev_b32_e32 v23, 16, v16
	v_cndmask_b32_e64 v44, v43, v39, s[44:45]
	v_cndmask_b32_e64 v46, v42, v38, s[44:45]
	v_cndmask_b32_e64 v39, v39, v43, s[44:45]
	v_cndmask_b32_e64 v38, v38, v42, s[44:45]
	v_mov_b32_e32 v22, v19
	v_add_f32_e32 v0, 1.0, v0
	v_cvt_pk_bf16_f32 v15, v38, v39
	v_rcp_f32_e32 v39, v0
	v_add_f32_e32 v0, 1.0, v10
	v_mov_b32_e32 v10, v23
	v_pk_mul_f32 v[22:23], v[30:31], v[22:23] op_sel_hi:[0,1]
	v_lshlrev_b32_e32 v11, 16, v24
	v_pk_fma_f32 v[18:19], v[26:27], v[18:19], v[22:23] op_sel_hi:[0,1,1]
	v_pk_fma_f32 v[10:11], v[34:35], v[10:11], v[18:19] op_sel_hi:[0,1,1]
	v_mul_f32_e32 v18, 0xbfb8aa3b, v10
	v_exp_f32_e32 v18, v18
	v_mul_f32_e32 v19, 0xbfb8aa3b, v11
	v_exp_f32_e32 v19, v19
	v_rcp_f32_e32 v38, v0
	v_add_f32_e32 v0, 1.0, v18
	v_rcp_f32_e32 v18, v0
	v_add_f32_e32 v0, 1.0, v19
	v_rcp_f32_e32 v19, v0
	v_cvt_pk_bf16_f32 v14, v44, v46
	v_cvt_pk_bf16_f32 v3, v41, v3
	ds_write2_b64 v40, v[14:15], v[2:3] offset0:36 offset1:54
	v_pk_mul_f32 v[2:3], v[6:7], v[38:39]
	v_pk_mul_f32 v[6:7], v[10:11], v[18:19]
	v_and_b32_e32 v11, 0xffff0000, v20
	v_cndmask_b32_e64 v22, v6, v2, s[44:45]
	v_cndmask_b32_e64 v38, v2, v6, s[44:45]
	v_and_b32_e32 v2, 0xffff0000, v12
	v_cndmask_b32_e64 v0, v7, v3, s[44:45]
	v_cndmask_b32_e64 v23, v3, v7, s[44:45]
	v_and_b32_e32 v6, 0xffff0000, v8
	v_mov_b32_e32 v7, v2
	v_and_b32_e32 v3, 0xffff0000, v4
	v_mov_b32_e32 v10, v6
	v_pk_mul_f32 v[6:7], v[30:31], v[6:7] op_sel:[1,0]
	v_and_b32_e32 v15, 0xffff0000, v16
	v_pk_fma_f32 v[2:3], v[26:27], v[2:3], v[6:7] op_sel:[1,0,0]
	v_mov_b32_e32 v14, v11
	v_pk_fma_f32 v[2:3], v[34:35], v[10:11], v[2:3] op_sel:[1,1,0] op_sel_hi:[1,0,1]
	v_and_b32_e32 v7, 0xffff0000, v24
	v_mul_f32_e32 v4, 0xbfb8aa3b, v3
	v_exp_f32_e32 v4, v4
	v_mul_f32_e32 v6, 0xbfb8aa3b, v2
	v_exp_f32_e32 v8, v6
	v_mov_b32_e32 v6, v15
	v_pk_mul_f32 v[14:15], v[30:31], v[14:15] op_sel:[1,0]
	v_add_f32_e32 v4, 1.0, v4
	v_pk_fma_f32 v[10:11], v[26:27], v[10:11], v[14:15] op_sel:[1,0,0]
	v_rcp_f32_e32 v19, v4
	v_pk_fma_f32 v[6:7], v[34:35], v[6:7], v[10:11] op_sel:[1,0,0]
	v_add_f32_e32 v4, 1.0, v8
	v_mul_f32_e32 v8, 0xbfb8aa3b, v6
	v_exp_f32_e32 v8, v8
	v_mul_f32_e32 v10, 0xbfb8aa3b, v7
	v_exp_f32_e32 v11, v10
	v_rcp_f32_e32 v18, v4
	v_add_f32_e32 v4, 1.0, v8
	v_rcp_f32_e32 v10, v4
	v_add_f32_e32 v4, 1.0, v11
	v_rcp_f32_e32 v11, v4
	v_pk_mul_f32 v[2:3], v[2:3], v[18:19]
	v_cvt_pk_bf16_f32 v14, v0, v22
	v_lshlrev_b32_e32 v19, 16, v21
	v_pk_mul_f32 v[6:7], v[6:7], v[10:11]
	v_lshlrev_b32_e32 v10, 16, v9
	v_cndmask_b32_e64 v4, v6, v2, s[44:45]
	v_cndmask_b32_e64 v8, v2, v6, s[44:45]
	v_lshlrev_b32_e32 v6, 16, v13
	v_mov_b32_e32 v11, v6
	v_cndmask_b32_e64 v0, v7, v3, s[44:45]
	v_cndmask_b32_e64 v3, v3, v7, s[44:45]
	v_lshlrev_b32_e32 v7, 16, v5
	v_mov_b32_e32 v18, v10
	v_pk_mul_f32 v[10:11], v[32:33], v[10:11] op_sel_hi:[0,1]
	v_pk_fma_f32 v[6:7], v[28:29], v[6:7], v[10:11] op_sel_hi:[0,1,1]
	v_pk_fma_f32 v[6:7], v[36:37], v[18:19], v[6:7] op_sel:[0,1,0] op_sel_hi:[0,0,1]
	v_cvt_pk_bf16_f32 v2, v0, v4
	v_mul_f32_e32 v0, 0xbfb8aa3b, v7
	v_exp_f32_e32 v0, v0
	v_mul_f32_e32 v4, 0xbfb8aa3b, v6
	v_cvt_pk_bf16_f32 v15, v38, v23
	v_lshlrev_b32_e32 v23, 16, v17
	v_exp_f32_e32 v4, v4
	v_mov_b32_e32 v22, v19
	v_mov_b32_e32 v10, v23
	v_pk_mul_f32 v[22:23], v[32:33], v[22:23] op_sel_hi:[0,1]
	v_lshlrev_b32_e32 v11, 16, v25
	v_pk_fma_f32 v[18:19], v[28:29], v[18:19], v[22:23] op_sel_hi:[0,1,1]
	v_add_f32_e32 v0, 1.0, v0
	v_pk_fma_f32 v[10:11], v[36:37], v[10:11], v[18:19] op_sel_hi:[0,1,1]
	v_rcp_f32_e32 v27, v0
	v_add_f32_e32 v0, 1.0, v4
	v_mul_f32_e32 v4, 0xbfb8aa3b, v10
	v_exp_f32_e32 v4, v4
	v_mul_f32_e32 v12, 0xbfb8aa3b, v11
	v_exp_f32_e32 v12, v12
	v_rcp_f32_e32 v26, v0
	v_add_f32_e32 v0, 1.0, v4
	v_rcp_f32_e32 v18, v0
	v_add_f32_e32 v0, 1.0, v12
	v_rcp_f32_e32 v19, v0
	v_cvt_pk_bf16_f32 v3, v8, v3
	ds_write2_b64 v40, v[14:15], v[2:3] offset0:72 offset1:90
	v_pk_mul_f32 v[2:3], v[6:7], v[26:27]
	v_pk_mul_f32 v[6:7], v[10:11], v[18:19]
	v_and_b32_e32 v4, 0xffff0000, v9
	v_cndmask_b32_e64 v15, v6, v2, s[44:45]
	v_cndmask_b32_e64 v18, v2, v6, s[44:45]
	v_and_b32_e32 v2, 0xffff0000, v13
	v_cndmask_b32_e64 v14, v7, v3, s[44:45]
	v_cndmask_b32_e64 v16, v3, v7, s[44:45]
	v_and_b32_e32 v3, 0xffff0000, v5
	v_mov_b32_e32 v5, v2
	v_mov_b32_e32 v10, v33
	v_mov_b32_e32 v6, v4
	v_mov_b32_e32 v0, v29
	v_pk_mul_f32 v[4:5], v[10:11], v[4:5] op_sel_hi:[0,1]
	v_and_b32_e32 v7, 0xffff0000, v21
	v_pk_fma_f32 v[2:3], v[0:1], v[2:3], v[4:5] op_sel_hi:[0,1,1]
	v_mov_b32_e32 v12, v37
	v_pk_fma_f32 v[2:3], v[12:13], v[6:7], v[2:3] op_sel:[0,1,0] op_sel_hi:[0,0,1]
	v_mul_f32_e32 v4, 0xbfb8aa3b, v3
	v_exp_f32_e32 v11, v4
	v_mul_f32_e32 v4, 0xbfb8aa3b, v2
	v_exp_f32_e32 v13, v4
	v_and_b32_e32 v9, 0xffff0000, v17
	v_add_f32_e32 v11, 1.0, v11
	v_rcp_f32_e32 v11, v11
	v_mov_b32_e32 v8, v7
	v_mov_b32_e32 v4, v9
	v_and_b32_e32 v5, 0xffff0000, v25
	v_pk_mul_f32 v[8:9], v[10:11], v[8:9] op_sel_hi:[0,1]
	v_add_f32_e32 v13, 1.0, v13
	v_pk_fma_f32 v[6:7], v[0:1], v[6:7], v[8:9] op_sel_hi:[0,1,1]
	v_pk_fma_f32 v[4:5], v[12:13], v[4:5], v[6:7] op_sel_hi:[0,1,1]
	v_mul_f32_e32 v0, 0xbfb8aa3b, v4
	v_exp_f32_e32 v0, v0
	v_mul_f32_e32 v6, 0xbfb8aa3b, v5
	v_exp_f32_e32 v7, v6
	v_rcp_f32_e32 v10, v13
	v_add_f32_e32 v0, 1.0, v0
	v_rcp_f32_e32 v6, v0
	v_add_f32_e32 v0, 1.0, v7
	v_rcp_f32_e32 v7, v0
	v_pk_mul_f32 v[2:3], v[2:3], v[10:11]
	v_cvt_pk_bf16_f32 v8, v14, v15
	v_cvt_pk_bf16_f32 v9, v18, v16
	v_pk_mul_f32 v[4:5], v[4:5], v[6:7]
	s_nop 0
	v_cndmask_b32_e64 v0, v5, v3, s[44:45]
	v_cndmask_b32_e64 v6, v4, v2, s[44:45]
	v_cndmask_b32_e64 v3, v3, v5, s[44:45]
	v_cndmask_b32_e64 v4, v2, v4, s[44:45]
	v_cvt_pk_bf16_f32 v2, v0, v6
	v_cvt_pk_bf16_f32 v3, v4, v3
	ds_write2_b64 v40, v[8:9], v[2:3] offset0:108 offset1:126
	s_and_saveexec_b64 s[0:1], s[46:47]
	s_cbranch_execz .LBB0_598
	v_lshl_or_b32 v0, v164, 3, v163
	v_lshlrev_b32_e32 v0, 2, v0
	s_waitcnt lgkmcnt(0)
	v_mov_b32_e32 v2, s101
	s_mov_b32 s2, 0x41a00000
	s_waitcnt vmcnt(0)
	v_add_f32_e32 v2, v166, v2
	v_cmp_nlt_f32_e32 vcc, s2, v2
	s_and_saveexec_b64 s[22:23], vcc
	s_cbranch_execz .LBB0_597
	v_mul_f32_e32 v3, 0x3fb8aa3b, v2
	v_rndne_f32_e32 v4, v3
	s_mov_b32 s2, 0x3fb8aa3b
	v_sub_f32_e32 v5, v3, v4
	v_fma_f32 v3, v2, s2, -v3
	v_fmac_f32_e32 v3, 0x32a5705f, v2
	v_add_f32_e32 v3, v5, v3
	v_cvt_i32_f32_e32 v4, v4
	v_exp_f32_e32 v3, v3
	s_mov_b32 s2, 0xc2ce8ed0
	v_cmp_ngt_f32_e32 vcc, s2, v2
	s_mov_b32 s2, 0x42b17218
	v_ldexp_f32 v3, v3, v4
	v_cndmask_b32_e32 v3, 0, v3, vcc
	v_cmp_nlt_f32_e32 vcc, s2, v2
	s_mov_b32 s2, 0x3f2aaaab
	s_nop 0
	v_cndmask_b32_e32 v16, v239, v3, vcc
	v_add_f32_e32 v4, 1.0, v16
	v_add_f32_e32 v2, -1.0, v4
	v_sub_f32_e32 v3, v2, v4
	v_add_f32_e32 v3, 1.0, v3
	v_sub_f32_e32 v2, v16, v2
	v_add_f32_e32 v5, v2, v3
	v_frexp_mant_f32_e32 v6, v4
	v_cvt_f64_f32_e32 v[2:3], v4
	v_frexp_exp_i32_f64_e32 v2, v[2:3]
	v_cmp_gt_f32_e32 vcc, s2, v6
	s_mov_b32 s2, 0x3f317218
	s_nop 0
	v_subbrev_co_u32_e32 v10, vcc, 0, v2, vcc
	v_sub_u32_e32 v2, 0, v10
	v_ldexp_f32 v3, v4, v2
	v_add_f32_e32 v4, -1.0, v3
	v_add_f32_e32 v6, 1.0, v3
	v_ldexp_f32 v2, v5, v2
	v_add_f32_e32 v5, 1.0, v4
	v_add_f32_e32 v7, -1.0, v6
	v_sub_f32_e32 v5, v3, v5
	v_sub_f32_e32 v3, v3, v7
	v_add_f32_e32 v5, v2, v5
	v_add_f32_e32 v2, v2, v3
	v_add_f32_e32 v11, v6, v2
	v_rcp_f32_e32 v13, v11
	v_sub_f32_e32 v3, v6, v11
	v_add_f32_e32 v12, v2, v3
	v_add_f32_e32 v3, v4, v5
	v_mul_f32_e32 v15, v3, v13
	v_sub_f32_e32 v2, v4, v3
	v_mul_f32_e32 v4, v11, v15
	v_fma_f32 v6, v15, v11, -v4
	v_fmac_f32_e32 v6, v15, v12
	v_add_f32_e32 v14, v5, v2
	v_add_f32_e32 v2, v4, v6
	v_sub_f32_e32 v5, v3, v2
	v_pk_add_f32 v[8:9], v[2:3], v[4:5] neg_lo:[0,1] neg_hi:[0,1]
	v_mov_b32_e32 v7, v2
	v_pk_add_f32 v[2:3], v[8:9], v[6:7] neg_lo:[0,1] neg_hi:[0,1]
	s_nop 0
	v_add_f32_e32 v3, v14, v3
	v_add_f32_e32 v2, v2, v3
	v_add_f32_e32 v3, v5, v2
	v_mul_f32_e32 v14, v13, v3
	v_mul_f32_e32 v4, v11, v14
	v_fma_f32 v6, v14, v11, -v4
	v_fmac_f32_e32 v6, v14, v12
	v_sub_f32_e32 v5, v5, v3
	v_add_f32_e32 v11, v2, v5
	v_add_f32_e32 v2, v4, v6
	v_sub_f32_e32 v5, v3, v2
	v_pk_add_f32 v[8:9], v[2:3], v[4:5] neg_lo:[0,1] neg_hi:[0,1]
	v_mov_b32_e32 v7, v2
	v_pk_add_f32 v[2:3], v[8:9], v[6:7] neg_lo:[0,1] neg_hi:[0,1]
	s_nop 0
	v_add_f32_e32 v3, v11, v3
	v_add_f32_e32 v2, v2, v3
	v_add_f32_e32 v3, v15, v14
	v_add_f32_e32 v2, v5, v2
	v_sub_f32_e32 v4, v3, v15
	v_mul_f32_e32 v2, v13, v2
	v_sub_f32_e32 v4, v14, v4
	v_add_f32_e32 v4, v4, v2
	v_add_f32_e32 v6, v3, v4
	v_mul_f32_e32 v7, v6, v6
	v_fmamk_f32 v2, v7, 0x3e9b6dac, v231
	v_fmaak_f32 v203, v7, v2, 0x3f2aaada
	v_cvt_f32_i32_e32 v2, v10
	v_sub_f32_e32 v3, v6, v3
	v_sub_f32_e32 v3, v4, v3
	v_ldexp_f32 v8, v3, 1
	v_mul_f32_e32 v3, v6, v7
	v_ldexp_f32 v5, v6, 1
	v_pk_mul_f32 v[6:7], v[2:3], v[202:203]
	s_nop 0
	v_fma_f32 v4, v2, s2, -v6
	v_fmac_f32_e32 v4, 0xb102e308, v2
	v_pk_add_f32 v[2:3], v[6:7], v[4:5]
	s_mov_b32 s2, 0x7f800000
	v_sub_f32_e32 v5, v3, v5
	v_sub_f32_e32 v5, v7, v5
	v_add_f32_e32 v9, v8, v5
	v_mov_b32_e32 v8, v6
	v_pk_add_f32 v[6:7], v[2:3], v[6:7] neg_lo:[0,1] neg_hi:[0,1]
	v_pk_add_f32 v[10:11], v[2:3], v[8:9]
	v_mov_b32_e32 v5, v2
	v_mov_b32_e32 v7, v11
	v_pk_add_f32 v[12:13], v[4:5], v[6:7] neg_lo:[0,1] neg_hi:[0,1]
	v_pk_add_f32 v[4:5], v[4:5], v[6:7]
	v_mov_b32_e32 v8, v9
	v_pk_add_f32 v[6:7], v[4:5], v[2:3] op_sel:[1,0] op_sel_hi:[0,1] neg_lo:[0,1] neg_hi:[0,1]
	v_pk_add_f32 v[14:15], v[10:11], v[6:7] op_sel_hi:[1,0] neg_lo:[0,1] neg_hi:[0,1]
	v_mov_b32_e32 v10, v11
	v_mov_b32_e32 v11, v5
	v_pk_mov_b32 v[6:7], v[2:3], v[6:7] op_sel:[1,0]
	v_mov_b32_e32 v9, v2
	v_pk_add_f32 v[6:7], v[10:11], v[6:7] neg_lo:[0,1] neg_hi:[0,1]
	v_mov_b32_e32 v14, v12
	v_pk_add_f32 v[2:3], v[8:9], v[6:7] neg_lo:[0,1] neg_hi:[0,1]
	v_mov_b32_e32 v13, v5
	v_pk_add_f32 v[6:7], v[14:15], v[2:3]
	v_cmp_neq_f32_e32 vcc, s2, v16
	v_pk_add_f32 v[8:9], v[6:7], v[6:7] op_sel:[0,1] op_sel_hi:[1,0]
	s_mov_b32 s2, 0x33800000
	v_pk_add_f32 v[4:5], v[4:5], v[8:9] op_sel:[1,0] op_sel_hi:[0,1]
	v_mov_b32_e32 v7, v4
	v_pk_add_f32 v[10:11], v[6:7], v[12:13] neg_lo:[0,1] neg_hi:[0,1]
	v_mov_b32_e32 v3, v8
	v_sub_f32_e32 v5, v6, v10
	v_pk_add_f32 v[2:3], v[2:3], v[10:11] neg_lo:[0,1] neg_hi:[0,1]
	v_sub_f32_e32 v5, v12, v5
	v_add_f32_e32 v2, v2, v5
	v_add_f32_e32 v2, v2, v3
	v_add_f32_e32 v2, v4, v2
	v_cndmask_b32_e32 v2, v239, v2, vcc
	v_cmp_lt_f32_e64 vcc, |v16|, s2
	s_nop 1
	v_cndmask_b32_e32 v2, v2, v16, vcc

.Lsb_nopend:
	s_setprio 0
	s_barrier
	ds_read_b32 v0, v158
	v_lshlrev_b32_e32 v60, 6, v147
	v_xor_b32_e32 v60, v60, v148
	v_ashrrev_i32_e32 v51, 6, v60
	v_and_b32_e32 v52, 31, v148
	v_and_b32_e32 v59, 1, v51
	v_lshrrev_b32_e32 v53, 5, v160
	v_lshl_or_b32 v55, v59, 5, v52
	v_ashrrev_i32_e32 v60, 7, v60
	v_cmp_ne_u32_e64 s[44:45], 1, v51
	v_mov_b32_e32 v2, 0
	v_lshlrev_b32_e32 v54, 4, v53
	v_mul_u32_u24_e32 v18, 0x110, v55
	v_mov_b32_e32 v3, 0
	v_mov_b32_e32 v4, 0
	v_mov_b32_e32 v5, 0
	v_mov_b32_e32 v6, 0
	v_mov_b32_e32 v7, 0
	v_mov_b32_e32 v8, 0
	v_mov_b32_e32 v9, 0
	v_mov_b32_e32 v10, 0
	v_mov_b32_e32 v11, 0
	v_mov_b32_e32 v12, 0
	v_mov_b32_e32 v13, 0
	v_mov_b32_e32 v14, 0
	v_mov_b32_e32 v15, 0
	v_mov_b32_e32 v16, 0
	v_mov_b32_e32 v17, 0
	s_and_saveexec_b64 s[0:1], s[44:45]
	s_cbranch_execz .LBB0_600
	v_lshl_or_b32 v2, v60, 5, v52
	v_mul_lo_u32 v2, v2, s14
	v_add3_u32 v10, v146, v2, v54
	v_add3_u32 v11, v146, v18, v54
	ds_read_b128 v[2:5], v10 offset:17408
	ds_read_b128 v[20:23], v10 offset:17440
	ds_read_b128 v[6:9], v11 offset:17408
	ds_read_b128 v[24:27], v11 offset:17440
	ds_read_b128 v[28:31], v10 offset:17472
	ds_read_b128 v[32:35], v10 offset:17504
	ds_read_b128 v[36:39], v11 offset:17472
	ds_read_b128 v[40:43], v11 offset:17504
	ds_read_b128 v[44:47], v10 offset:17536
	ds_read_b128 v[62:65], v10 offset:17568
	ds_read_b128 v[66:69], v11 offset:17536
	ds_read_b128 v[70:73], v11 offset:17568
	ds_read_b128 v[74:77], v10 offset:17600
	ds_read_b128 v[78:81], v10 offset:17632
	ds_read_b128 v[82:85], v11 offset:17600
	ds_read_b128 v[86:89], v11 offset:17632
	s_waitcnt lgkmcnt(13)
	v_mfma_f32_32x32x16_bf16 v[2:17], v[2:5], v[6:9], 0
	s_waitcnt lgkmcnt(12)
	v_mfma_f32_32x32x16_bf16 v[2:17], v[20:23], v[24:27], v[2:17]
	s_waitcnt lgkmcnt(9)
	v_mfma_f32_32x32x16_bf16 v[2:17], v[28:31], v[36:39], v[2:17]
	s_waitcnt lgkmcnt(8)
	v_mfma_f32_32x32x16_bf16 v[2:17], v[32:35], v[40:43], v[2:17]
	s_waitcnt lgkmcnt(5)
	v_mfma_f32_32x32x16_bf16 v[2:17], v[44:47], v[66:69], v[2:17]
	s_waitcnt lgkmcnt(4)
	v_mfma_f32_32x32x16_bf16 v[2:17], v[62:65], v[70:73], v[2:17]
	s_waitcnt lgkmcnt(1)
	v_mfma_f32_32x32x16_bf16 v[2:17], v[74:77], v[82:85], v[2:17]
	s_waitcnt lgkmcnt(0)
	v_mfma_f32_32x32x16_bf16 v[2:17], v[78:81], v[86:89], v[2:17]
